# lever 4: one static s_setprio 1 for waves 4..7 at the entry of the diff and stick-breaking units (reset at the next work fetch)
# baseline (speedup 1.0000x reference)
.Lmx_sb_go:
	v_readfirstlane_b32 s98, v214
	s_cmpk_lt_u32 s98, 0x100
	s_cbranch_scc1 .Lprio_sb
	s_setprio 1

.LBB0_614:
	s_setprio 0
	s_and_saveexec_b64 s[10:11], s[8:9]
	s_cbranch_execz .LBB0_434
	s_mov_b64 s[14:15], exec
	v_mbcnt_lo_u32_b32 v0, s14, 0
	v_mbcnt_hi_u32_b32 v0, s15, v0
	v_cmp_eq_u32_e32 vcc, 0, v0
	s_and_saveexec_b64 s[12:13], vcc
	s_cbranch_execz .LBB0_433
	s_bcnt1_i32_b64 s4, s[14:15]
	v_mov_b32_e32 v1, s4
	global_atomic_add v1, v193, v1, s[62:63] sc0
	s_branch .LBB0_433
